# attention: one workgroup barrier per KV tile (4-slot K/V LDS ring, halves offset by half an iteration)
# speedup vs baseline: 1.0180x; 1.0042x over previous
; #define AT_LOAD(t) do { kr0 = *(const u32x4*)(Kp + (size_t)((t) * 64 + kkey0) * 96 + kc0 * 8); if (k1ok) kr1 = *(const u32x4*)(Kp + (size_t)((t) * 64 + kkey1) * 96 + kc1 * 8); \
;         vr = *(const u32x4*)(Vtp + (size_t)vd * KVLEN + (t) * 64 + vc * 8); } while (0)
; #define AT_STORE(bf) do { *(u32x4*)(Kl + (bf) * AT_KB + kkey0 * AT_KP + kc0 * 16) = kr0; if (k1ok) *(u32x4*)(Kl + (bf) * AT_KB + kkey1 * AT_KP + kc1 * 16) = kr1; \
;         *(u32x2*)(Vl + (bf) * AT_VB + vd * AT_VP + vc * 16) = (u32x2){vr.x, vr.y}; *(u32x2*)(Vl + (bf) * AT_VB + vd * AT_VP + vc * 16 + 8) = (u32x2){vr.z, vr.w}; } while (0)
; DI void attn_unit(int tb_, char* shm, const bf16_t* Qp, const bf16_t* Kp, const bf16_t* Vtp, int nkeys, int nrows, bf16_t* Op) {
;     ...
;     const int kkey0 = tid / 12, kc0 = tid % 12, kkey1 = (tid + 512) / 12, kc1 = (tid + 512) % 12; const bool k1ok = tid < 256;
;     const int vd = tid >> 3, vc = tid & 7;
;     u32x4 kr0, kr1, vr; kr1 = (u32x4){0u, 0u, 0u, 0u};
;     ...
;     const int nt = nkeys >> 6;
;     f32x16 oa0, oa1, ob0, ob1;
; #pragma unroll
;     for (int r = 0; r < 16; ++r) { oa0[r] = 0.f; oa1[r] = 0.f; ob0[r] = 0.f; ob1[r] = 0.f; }
;     float mra = -INFINITY, lsa = 0.f, mrb = -INFINITY, lsb = 0.f;
;     AT_LOAD(0); AT_STORE(0); __syncthreads();
.LBB0_1042:
	s_or_b64 exec, exec, s[20:21]
	s_mul_i32 s20, s34, 0x88000
	s_mul_hi_i32 s21, s34, 0x88000
	s_add_u32 s6, s28, s20
	s_addc_u32 s7, s29, s21
	v_and_b32_e32 v6, 7, v14
	v_ashrrev_i32_e32 v18, 3, v14
	v_mov_b64_e32 v[4:5], s[6:7]
	s_movk_i32 s0, 0x2200
	v_mad_i64_i32 v[4:5], s[6:7], v18, s0, v[4:5]
	v_lshlrev_b32_e32 v12, 4, v6
	v_mov_b32_e32 v13, v189
	v_lshl_add_u64 v[4:5], v[4:5], 0, v[12:13]
	global_load_dwordx4 v[4:7], v[4:5], off
	s_movk_i32 s0, 0xd0
	v_mul_lo_u32 v205, v16, s0
	v_lshlrev_b32_e32 v206, 4, v17
	v_add3_u32 v13, 0, v205, v206
	v_lshlrev_b32_e32 v207, 4, v19
	s_waitcnt vmcnt(0)
	ds_write_b128 v13, v[0:3]
	s_and_saveexec_b64 s[6:7], vcc
	s_xor_b64 s[6:7], exec, s[6:7]
	v_lshlrev_b32_e32 v207, 4, v19
	s_or_saveexec_b64 s[6:7], s[6:7]
	v_mul_lo_u32 v208, v15, s0
	s_xor_b64 exec, exec, s[6:7]
	v_add3_u32 v0, 0, v208, v207
	ds_write_b128 v0, v[176:179]
	s_or_b64 exec, exec, s[6:7]
	s_movk_i32 s36, 0xc0
	s_movk_i32 s0, 0x2200
	v_mad_i64_i32 v[0:1], s[6:7], v16, s36, 0
	v_mad_i64_i32 v[2:3], s[6:7], v18, s0, 0
	s_lshl_b32 s6, s33, 1
	s_and_b32 s6, s6, 0xffffff80
	s_add_i32 s33, s6, 0
	s_movk_i32 s6, 0x88
	v_mul_lo_u32 v16, v18, s6
	v_add3_u32 v209, 0, v16, v12
	v_and_b32_e32 v13, 63, v14
	v_add_u32_e32 v16, 0xe400, v209
	ds_write2_b64 v16, v[4:5], v[6:7] offset1:1
	s_movk_i32 s0, 0xd0
	v_lshlrev_b32_e32 v5, 2, v13
	v_lshlrev_b32_e32 v14, 3, v200
	v_mad_u32_u24 v4, v201, s0, 0
	v_xor_b32_e32 v202, 0x80, v5
	v_mul_i32_i24_e32 v5, 0xffffffb8, v201
	v_add_u32_e32 v210, v4, v188
	v_add3_u32 v204, v4, v5, v14
	v_mov_b64_e32 v[4:5], s[10:11]
	v_cmp_gt_u32_e64 s[6:7], 32, v13
	v_mad_i64_i32 v[4:5], s[36:37], v15, s36, v[4:5]
	v_lshl_add_u64 v[2:3], s[20:21], 0, v[2:3]
	v_mov_b32_e32 v13, v189
	v_lshl_add_u64 v[0:1], s[10:11], 0, v[0:1]
	v_lshl_add_u64 v[4:5], v[10:11], 1, v[4:5]
	v_lshl_add_u64 v[2:3], v[2:3], 0, v[12:13]
	v_lshl_add_u64 v[0:1], v[8:9], 1, v[0:1]
	v_mov_b32_e32 v32, v189
	v_mov_b32_e32 v33, v189
	v_mov_b32_e32 v46, v189
	v_mov_b32_e32 v47, v189
	v_lshl_add_u64 v[192:193], s[12:13], 0, v[4:5]
	v_lshl_add_u64 v[194:195], s[14:15], 0, v[2:3]
	v_lshl_add_u64 v[196:197], s[12:13], 0, v[0:1]
	v_mov_b32_e32 v34, v189
	v_mov_b32_e32 v35, v189
	v_mov_b32_e32 v36, v189
	v_mov_b32_e32 v37, v189
	v_mov_b32_e32 v38, v189
	v_mov_b32_e32 v39, v189
	v_mov_b32_e32 v40, v189
	v_mov_b32_e32 v41, v189
	v_mov_b32_e32 v42, v189
	v_mov_b32_e32 v43, v189
	v_mov_b32_e32 v44, v189
	v_mov_b32_e32 v45, v189
	v_mov_b64_e32 v[62:63], v[46:47]
	v_mov_b64_e32 v[16:17], v[32:33]
	v_mov_b64_e32 v[0:1], v[32:33]
	v_lshl_add_u32 v198, v201, 2, s33
	s_add_i32 s35, s35, 1
	s_mov_b32 s36, 0
	v_mov_b32_e32 v203, 0
	v_mov_b32_e32 v214, 0xff800000
	v_mov_b64_e32 v[60:61], v[44:45]
	v_mov_b64_e32 v[58:59], v[42:43]
	v_mov_b64_e32 v[56:57], v[40:41]
	v_mov_b64_e32 v[54:55], v[38:39]
	v_mov_b64_e32 v[52:53], v[36:37]
	v_mov_b64_e32 v[50:51], v[34:35]
	v_mov_b64_e32 v[48:49], v[32:33]
	v_mov_b64_e32 v[18:19], v[34:35]
	v_mov_b64_e32 v[20:21], v[36:37]
	v_mov_b64_e32 v[22:23], v[38:39]
	v_mov_b64_e32 v[24:25], v[40:41]
	v_mov_b64_e32 v[26:27], v[42:43]
	v_mov_b64_e32 v[28:29], v[44:45]
	v_mov_b64_e32 v[30:31], v[46:47]
	v_mov_b64_e32 v[2:3], v[34:35]
	v_mov_b64_e32 v[4:5], v[36:37]
	v_mov_b64_e32 v[6:7], v[38:39]
	v_mov_b64_e32 v[8:9], v[40:41]
	v_mov_b64_e32 v[10:11], v[42:43]
	v_mov_b64_e32 v[12:13], v[44:45]
	v_mov_b64_e32 v[14:15], v[46:47]
	v_mov_b32_e32 v213, 0xff800000
	v_mov_b32_e32 v199, 0
	s_waitcnt lgkmcnt(0)
	s_barrier
	global_load_dwordx4 v[184:187], v[196:197], off
	s_and_saveexec_b64 s[10:11], s[8:9]
	s_cbranch_execz .Lat2_pk1
	global_load_dwordx4 v[176:179], v[192:193], off
.Lat2_pk1:
	s_or_b64 exec, exec, s[10:11]
	v_lshl_add_u64 v[192:193], v[192:193], 0, s[86:87]
	v_lshl_add_u64 v[196:197], v[196:197], 0, s[86:87]
	global_load_dwordx4 v[180:183], v[194:195], off
	v_lshl_add_u64 v[194:195], v[194:195], 0, s[72:73]
	global_load_dwordx4 v[232:235], v[196:197], off
	s_and_saveexec_b64 s[10:11], s[8:9]
	s_cbranch_execz .Lat2_pk2
	global_load_dwordx4 v[250:253], v[192:193], off

; #define AT_LOAD(t) do { kr0 = *(const u32x4*)(Kp + (size_t)((t) * 64 + kkey0) * 96 + kc0 * 8); if (k1ok) kr1 = *(const u32x4*)(Kp + (size_t)((t) * 64 + kkey1) * 96 + kc1 * 8); \
;         vr = *(const u32x4*)(Vtp + (size_t)vd * KVLEN + (t) * 64 + vc * 8); } while (0)
; #define AT_STORE(bf) do { *(u32x4*)(Kl + (bf) * AT_KB + kkey0 * AT_KP + kc0 * 16) = kr0; if (k1ok) *(u32x4*)(Kl + (bf) * AT_KB + kkey1 * AT_KP + kc1 * 16) = kr1; \
;         *(u32x2*)(Vl + (bf) * AT_VB + vd * AT_VP + vc * 16) = (u32x2){vr.x, vr.y}; *(u32x2*)(Vl + (bf) * AT_VB + vd * AT_VP + vc * 16 + 8) = (u32x2){vr.z, vr.w}; } while (0)
; DI void attn_unit(int tb_, char* shm, const bf16_t* Qp, const bf16_t* Kp, const bf16_t* Vtp, int nkeys, int nrows, bf16_t* Op) {
;     ...
;     AT_LOAD(0); AT_STORE(0); __syncthreads();
;     for (int t = 0; t < nt; ++t) {
;         const int bf = t & 1;
;         if (t + 1 < nt) AT_LOAD(t + 1);
.Lat2_ps1_skip:
	s_waitcnt vmcnt(0)
	s_movk_i32 s38, 0x3400
	v_add3_u32 v228, s38, v205, v206
	ds_write_b128 v228, v[184:187]
	s_and_saveexec_b64 s[20:21], s[8:9]
	v_add3_u32 v228, s38, v208, v207
	ds_write_b128 v228, v[176:179]
	s_or_b64 exec, exec, s[20:21]
	s_mov_b32 s38, 0x6800
	v_add3_u32 v228, s38, v205, v206
	ds_write_b128 v228, v[232:235]
	s_and_saveexec_b64 s[20:21], s[8:9]
	v_add3_u32 v228, s38, v208, v207
	ds_write_b128 v228, v[250:253]
	s_or_b64 exec, exec, s[20:21]
	s_mov_b32 s38, 0x10600
	v_add_u32_e32 v228, s38, v209
	ds_write2_b64 v228, v[180:181], v[182:183] offset1:1
	global_load_dwordx4 v[184:187], v[196:197], off
	s_and_saveexec_b64 s[10:11], s[8:9]
	s_cbranch_execz .Lat2_pk3
	global_load_dwordx4 v[176:179], v[192:193], off
.Lat2_pk3:
	s_or_b64 exec, exec, s[10:11]
	v_lshl_add_u64 v[192:193], v[192:193], 0, s[86:87]
	v_lshl_add_u64 v[196:197], v[196:197], 0, s[86:87]
	global_load_dwordx4 v[180:183], v[194:195], off
	v_lshl_add_u64 v[194:195], v[194:195], 0, s[72:73]
	s_mov_b32 s36, 0
	s_waitcnt lgkmcnt(0)
	s_barrier

; DI void attn_unit(int tb_, char* shm, const bf16_t* Qp, const bf16_t* Kp, const bf16_t* Vtp, int nkeys, int nrows, bf16_t* Op) {
;     ...
;     for (int t = 0; t < nt; ++t) {
;         const int bf = t & 1;
;         if (t + 1 < nt) AT_LOAD(t + 1);
;         if (act) {
;             f32x16 pa0, pa1, pb0, pb1;
; #pragma unroll
;             for (int r = 0; r < 16; ++r) { pa0[r] = 0.f; pa1[r] = 0.f; pb0[r] = 0.f; pb1[r] = 0.f; }
;             const char* kb = Kl + bf * AT_KB + r32 * AT_KP + 16 * hi;
; #pragma unroll
;             for (int s = 0; s < 6; ++s) { const bf16x8 k0 = *(const bf16x8*)(kb + 32 * s); const bf16x8 k1 = *(const bf16x8*)(kb + 32 * AT_KP + 32 * s);
;                 pa0 = __builtin_amdgcn_mfma_f32_32x32x16_bf16(k0, qf0[s], pa0, 0, 0, 0); pa1 = __builtin_amdgcn_mfma_f32_32x32x16_bf16(k1, qf0[s], pa1, 0, 0, 0);
;                 pb0 = __builtin_amdgcn_mfma_f32_32x32x16_bf16(k0, qf1[s], pb0, 0, 0, 0); pb1 = __builtin_amdgcn_mfma_f32_32x32x16_bf16(k1, qf1[s], pb1, 0, 0, 0); }
;             bf16x8 qa[4], qb4[4];
;             AT_SM(pa0, pa1, oa0, oa1, mra, lsa, qa);
;             AT_SM(pb0, pb1, ob0, ob1, mrb, lsb, qb4);
;             __builtin_amdgcn_sched_barrier(0);
;             const char* vb = Vl + bf * AT_VB + r32 * AT_VP + 8 * hi;
; #pragma unroll
;             for (int kh = 0; kh < 2; ++kh) {
;                 u32x2 va0[2], va1[2], vc0[2], vc1[2];
; #pragma unroll
;                 for (int k2 = 0; k2 < 2; ++k2) { const int ks = 2 * kh + k2; va0[k2] = *(const u32x2*)(vb + 32 * ks); va1[k2] = *(const u32x2*)(vb + 32 * ks + 16); vc0[k2] = *(const u32x2*)(vb + 32 * AT_VP + 32 * ks); vc1[k2] = *(const u32x2*)(vb + 32 * AT_VP + 32 * ks + 16); }
; #pragma unroll
;                 for (int k2 = 0; k2 < 2; ++k2) { const int ks = 2 * kh + k2;
;                     const bf16x8 vfa = __builtin_bit_cast(bf16x8, ((u32x4){va0[k2].x, va0[k2].y, va1[k2].x, va1[k2].y})), vfc = __builtin_bit_cast(bf16x8, ((u32x4){vc0[k2].x, vc0[k2].y, vc1[k2].x, vc1[k2].y}));
;                     oa0 = __builtin_amdgcn_mfma_f32_32x32x16_bf16(qa[ks], vfa, oa0, 0, 0, 0); oa1 = __builtin_amdgcn_mfma_f32_32x32x16_bf16(qa[ks], vfc, oa1, 0, 0, 0);
;                     ob0 = __builtin_amdgcn_mfma_f32_32x32x16_bf16(qb4[ks], vfa, ob0, 0, 0, 0); ob1 = __builtin_amdgcn_mfma_f32_32x32x16_bf16(qb4[ks], vfc, ob1, 0, 0, 0); }
;                 __builtin_amdgcn_sched_barrier(0);
.Lat_val_skip:
	s_cmpk_lt_u32 s1, 0x100
	s_cbranch_scc1 .Lat2_nobar_b
	s_waitcnt lgkmcnt(0)
	s_barrier
.Lat2_nobar_b:
	s_setprio 1
	s_andn2_b64 vcc, exec, s[18:19]
	s_cbranch_vccnz .Lat_mm_skip
	s_and_b32 s20, s36, 3
	s_mul_i32 s20, s20, 0x2200
	v_add_u32_e32 v229, s20, v204
	v_add_u32_e32 v228, 0xe400, v229
	v_add_u32_e32 v229, 0xf400, v229
	ds_read2_b64 v[80:83], v228 offset1:2
	ds_read2_b64 v[84:87], v229 offset0:32 offset1:34
	ds_read2_b64 v[88:91], v228 offset0:4 offset1:6
	ds_read2_b64 v[92:95], v229 offset0:36 offset1:38
	ds_read2_b64 v[112:115], v228 offset0:8 offset1:10
	ds_read2_b64 v[116:119], v229 offset0:40 offset1:42
	ds_read2_b64 v[120:123], v228 offset0:12 offset1:14
	ds_read2_b64 v[124:127], v229 offset0:44 offset1:46
	s_waitcnt lgkmcnt(6)
	v_mfma_f32_32x32x16_bf16 v[32:47], v[100:103], v[80:83], v[32:47]
	v_mfma_f32_32x32x16_bf16 v[48:63], v[100:103], v[84:87], v[48:63]
	v_mfma_f32_32x32x16_bf16 v[16:31], v[64:67], v[80:83], v[16:31]
	v_mfma_f32_32x32x16_bf16 v[0:15], v[64:67], v[84:87], v[0:15]
	s_waitcnt lgkmcnt(4)
	v_mfma_f32_32x32x16_bf16 v[32:47], v[108:111], v[88:91], v[32:47]
	v_mfma_f32_32x32x16_bf16 v[48:63], v[108:111], v[92:95], v[48:63]
	v_mfma_f32_32x32x16_bf16 v[16:31], v[72:75], v[88:91], v[16:31]
	v_mfma_f32_32x32x16_bf16 v[0:15], v[72:75], v[92:95], v[0:15]
	s_waitcnt lgkmcnt(2)
	v_mfma_f32_32x32x16_bf16 v[32:47], v[104:107], v[112:115], v[32:47]
	v_mfma_f32_32x32x16_bf16 v[48:63], v[104:107], v[116:119], v[48:63]
	v_mfma_f32_32x32x16_bf16 v[16:31], v[68:71], v[112:115], v[16:31]
	v_mfma_f32_32x32x16_bf16 v[0:15], v[68:71], v[116:119], v[0:15]
	s_waitcnt lgkmcnt(0)
	v_mfma_f32_32x32x16_bf16 v[32:47], v[96:99], v[120:123], v[32:47]
	v_mfma_f32_32x32x16_bf16 v[48:63], v[96:99], v[124:127], v[48:63]
	v_mfma_f32_32x32x16_bf16 v[16:31], v[76:79], v[120:123], v[16:31]
	v_mfma_f32_32x32x16_bf16 v[0:15], v[76:79], v[124:127], v[0:15]
	s_cmp_lt_u32 s36, s35
	s_cbranch_scc0 .Lat_mm_skip
	s_add_i32 s20, s36, 1
	s_and_b32 s20, s20, 3
	s_mul_i32 s39, s20, 0x3400
	s_cmpk_eq_u32 s20, 3
	s_cselect_b32 s20, 0xb000, s39
	v_add_u32_e32 v92, s20, v210
	ds_read_b128 v[64:67], v92
	ds_read_b128 v[80:83], v92 offset:32
	ds_read_b128 v[84:87], v92 offset:6656
	ds_read_b128 v[216:219], v92 offset:6688
	s_waitcnt lgkmcnt(3)
	v_mfma_f32_32x32x16_bf16 v[96:111], v[64:67], v[172:175], 0
	v_mfma_f32_32x32x16_bf16 v[64:79], v[64:67], v[148:151], 0
	s_waitcnt lgkmcnt(2)
	v_mfma_f32_32x32x16_bf16 v[96:111], v[80:83], v[168:171], v[96:111]
	v_mfma_f32_32x32x16_bf16 v[64:79], v[80:83], v[140:143], v[64:79]
	ds_read_b128 v[80:83], v92 offset:64
	ds_read_b128 v[88:91], v92 offset:96
	ds_read_b128 v[220:223], v92 offset:6720
	ds_read_b128 v[224:227], v92 offset:6752
	s_waitcnt lgkmcnt(3)
	v_mfma_f32_32x32x16_bf16 v[96:111], v[80:83], v[164:167], v[96:111]
	v_mfma_f32_32x32x16_bf16 v[64:79], v[80:83], v[144:147], v[64:79]
	s_waitcnt lgkmcnt(2)
	v_mfma_f32_32x32x16_bf16 v[96:111], v[88:91], v[160:163], v[96:111]
	v_mfma_f32_32x32x16_bf16 v[64:79], v[88:91], v[136:139], v[64:79]
	ds_read_b128 v[80:83], v92 offset:128
	ds_read_b128 v[88:91], v92 offset:160
	ds_read_b128 v[242:245], v92 offset:6784
	ds_read_b128 v[246:249], v92 offset:6816
	v_mfma_f32_32x32x16_bf16 v[112:127], v[84:87], v[172:175], 0
	s_waitcnt lgkmcnt(3)
	v_mfma_f32_32x32x16_bf16 v[96:111], v[80:83], v[156:159], v[96:111]
	v_mfma_f32_32x32x16_bf16 v[64:79], v[80:83], v[132:135], v[64:79]
	v_mfma_f32_32x32x16_bf16 v[112:127], v[216:219], v[168:171], v[112:127]
	s_waitcnt lgkmcnt(2)
	v_mfma_f32_32x32x16_bf16 v[96:111], v[88:91], v[152:155], v[96:111]
	v_mfma_f32_32x32x16_bf16 v[64:79], v[88:91], v[128:131], v[64:79]
	v_mfma_f32_32x32x16_bf16 v[80:95], v[84:87], v[148:151], 0
	v_mfma_f32_32x32x16_bf16 v[112:127], v[220:223], v[164:167], v[112:127]
	v_mfma_f32_32x32x16_bf16 v[80:95], v[216:219], v[140:143], v[80:95]
	v_mfma_f32_32x32x16_bf16 v[112:127], v[224:227], v[160:163], v[112:127]
	v_mfma_f32_32x32x16_bf16 v[80:95], v[220:223], v[144:147], v[80:95]
	s_waitcnt lgkmcnt(1)
	v_mfma_f32_32x32x16_bf16 v[112:127], v[242:245], v[156:159], v[112:127]
	v_mfma_f32_32x32x16_bf16 v[80:95], v[224:227], v[136:139], v[80:95]
	s_waitcnt lgkmcnt(0)
	v_mfma_f32_32x32x16_bf16 v[112:127], v[246:249], v[152:155], v[112:127]
	v_mfma_f32_32x32x16_bf16 v[80:95], v[242:245], v[132:135], v[80:95]
	v_mfma_f32_32x32x16_bf16 v[80:95], v[246:249], v[128:131], v[80:95]
.Lat_mm_skip:
	s_setprio 0
	s_add_i32 s38, s36, 3
	s_and_b32 s38, s38, 3
	s_mul_i32 s39, s38, 0x3400
	s_cmpk_eq_u32 s38, 3
	s_cselect_b32 s38, 0xb000, s39
	s_waitcnt vmcnt(0)
	v_add3_u32 v228, s38, v205, v206
	ds_write_b128 v228, v[184:187]
	s_and_saveexec_b64 s[20:21], s[8:9]
	v_add3_u32 v228, s38, v208, v207
	ds_write_b128 v228, v[176:179]
	s_or_b64 exec, exec, s[20:21]
	s_add_i32 s38, s36, 2
	s_and_b32 s38, s38, 3
	s_mul_i32 s38, s38, 0x2200
	s_add_i32 s38, s38, 0xe400
	v_add_u32_e32 v228, s38, v209
	ds_write2_b64 v228, v[180:181], v[182:183] offset1:1
	global_load_dwordx4 v[184:187], v[196:197], off
	s_and_saveexec_b64 s[10:11], s[8:9]
	s_cbranch_execz .Lat_k1
	global_load_dwordx4 v[176:179], v[192:193], off
.Lat_k1:
	s_or_b64 exec, exec, s[10:11]
	v_lshl_add_u64 v[192:193], v[192:193], 0, s[86:87]
	v_lshl_add_u64 v[196:197], v[196:197], 0, s[86:87]
	global_load_dwordx4 v[180:183], v[194:195], off
	v_lshl_add_u64 v[194:195], v[194:195], 0, s[72:73]
	s_add_i32 s36, s36, 1
	s_cmpk_lt_u32 s1, 0x100
	s_cbranch_scc0 .Lat2_nobar_a
	s_waitcnt lgkmcnt(0)
	s_barrier
.Lat2_nobar_a:
	s_cmp_le_u32 s36, s35
	s_cbranch_scc1 .Lat_loop
